# P0 balanced per workgroup: even waves convert one layer-0 in/out weight tile each, every wave 8 x rows (8-row batch), on top of the shared layer-0 conversion slot
# speedup vs baseline: 1.0038x; 1.0011x over previous
.LBB0_24:
	v_writelane_b32 v253, s36, 42
	s_nop 1
	v_writelane_b32 v253, s37, 43
	v_writelane_b32 v253, s34, 44
	s_nop 1
	v_writelane_b32 v253, s35, 45
	s_or_b64 exec, exec, s[4:5]
	s_load_dwordx16 s[12:27], s[0:1], 0x0
	s_lshl_b32 s38, s78, 3
	s_waitcnt lgkmcnt(0)
	v_writelane_b32 v253, s12, 26
	s_nop 1
	v_writelane_b32 v253, s13, 27
	v_writelane_b32 v253, s14, 28
	v_writelane_b32 v253, s15, 29
	v_writelane_b32 v253, s16, 30
	v_writelane_b32 v253, s17, 31
	v_writelane_b32 v253, s18, 32
	v_writelane_b32 v253, s19, 33
	v_writelane_b32 v253, s20, 34
	v_writelane_b32 v253, s21, 35
	v_writelane_b32 v253, s22, 36
	v_writelane_b32 v253, s23, 37
	v_writelane_b32 v253, s24, 38
	v_writelane_b32 v253, s25, 39
	v_writelane_b32 v253, s26, 40
	v_writelane_b32 v253, s27, 41
	s_load_dwordx16 s[12:27], s[0:1], 0x40
	s_lshr_b32 s0, s8, 6
	s_lshl_b32 s1, s2, 3
	s_add_i32 s36, s0, s1
	s_waitcnt lgkmcnt(0)
	v_writelane_b32 v253, s12, 10
	s_nop 1
	v_writelane_b32 v253, s13, 11
	v_writelane_b32 v253, s14, 12
	v_writelane_b32 v253, s15, 13
	v_writelane_b32 v253, s16, 14
	v_writelane_b32 v253, s17, 15
	v_writelane_b32 v253, s18, 16
	v_writelane_b32 v253, s19, 17
	v_writelane_b32 v253, s20, 18
	v_writelane_b32 v253, s21, 19
	v_writelane_b32 v253, s22, 20
	v_writelane_b32 v253, s23, 21
	v_writelane_b32 v253, s24, 22
	v_writelane_b32 v253, s25, 23
	v_writelane_b32 v253, s26, 24
	v_writelane_b32 v253, s27, 25
	s_nop 0
	v_readlane_b32 s8, v253, 0
	v_readlane_b32 s10, v253, 2
	v_readlane_b32 s11, v253, 3
	s_add_u32 s64, s10, 0x400000
	s_addc_u32 s65, s11, 0
	s_cmpk_gt_i32 s36, 0x2fff
	v_readlane_b32 s9, v253, 1
	s_cbranch_scc1 .LBB0_178
	v_and_b32_e32 v219, 31, v227
	v_lshlrev_b32_e32 v212, 4, v219
	v_lshrrev_b32_e32 v213, 5, v227
	v_lshlrev_b32_e32 v214, 2, v219
	v_and_b32_e32 v215, 64, v214
	v_add_u32_e32 v215, v215, v214
	v_lshlrev_b32_e32 v216, 5, v213
	v_readlane_b32 s8, v253, 36
	v_readlane_b32 s9, v253, 37
	v_readlane_b32 s10, v253, 34
	v_readlane_b32 s11, v253, 35
	v_readlane_b32 s12, v253, 16
	v_readlane_b32 s13, v253, 17
	v_readlane_b32 s14, v253, 18
	v_readlane_b32 s15, v253, 19
	v_readlane_b32 s16, v253, 20
	v_readlane_b32 s17, v253, 21
	v_readlane_b32 s18, v253, 22
	v_readlane_b32 s19, v253, 23
	s_mov_b32 s66, s36
	s_movk_i32 s98, 0x17ff
	s_mov_b32 s99, s38
	s_cmpk_eq_u32 s78, 0x100
	s_cbranch_scc0 .Lwt_loop
	s_movk_i32 s98, 0x3ff
	s_movk_i32 s99, 0x400
	s_bitcmp0_b32 s36, 0
	s_cselect_b32 s67, 0, 0x7fff
	s_lshr_b32 s66, s36, 1
	s_or_b32 s66, s66, s67

.Lwt_done:
.LBB0_178:
	v_readlane_b32 s8, v253, 0
	v_readlane_b32 s10, v253, 2
	v_readlane_b32 s11, v253, 3
	s_add_u32 s46, s10, 0x3400000
	s_addc_u32 s47, s11, 0
	s_cmpk_lt_i32 s36, 0x4200
	s_cselect_b64 s[0:1], -1, 0
	v_readlane_b32 s9, v253, 1
	v_writelane_b32 v253, s0, 46
	s_cmpk_gt_i32 s36, 0x41ff
	v_mbcnt_lo_u32_b32 v42, -1, 0
	v_writelane_b32 v253, s1, 47
	s_cbranch_scc1 .LBB0_192
	v_mbcnt_hi_u32_b32 v3, -1, v42
	s_ashr_i32 s39, s38, 31
	v_lshlrev_b32_e32 v4, 4, v227
	v_lshlrev_b32_e32 v5, 3, v227
	v_mov_b32_e32 v12, 0
	v_xor_b32_e32 v6, 1, v227
	v_lshlrev_b32_e32 v6, 2, v6
	v_xor_b32_e32 v7, 2, v227
	v_lshlrev_b32_e32 v7, 2, v7
	v_xor_b32_e32 v8, 4, v227
	v_lshlrev_b32_e32 v8, 2, v8
	v_xor_b32_e32 v9, 8, v227
	v_lshlrev_b32_e32 v9, 2, v9
	v_xor_b32_e32 v10, 16, v227
	v_lshlrev_b32_e32 v10, 2, v10
	v_xor_b32_e32 v11, 32, v227
	v_lshlrev_b32_e32 v11, 2, v11
	v_readlane_b32 s48, v253, 26
	v_readlane_b32 s49, v253, 27
	v_readlane_b32 s50, v253, 28
	v_readlane_b32 s51, v253, 29
	v_readlane_b32 s52, v253, 44
	v_readlane_b32 s53, v253, 45
	s_mov_b32 s14, s36
	s_movk_i32 s98, 0x4200
	s_mov_b32 s99, s38
.Lxn_loop:
	s_cmp_lt_i32 s14, s98
	s_cbranch_scc0 .Lxn_done
	s_mul_i32 s15, s99, 7
	s_add_i32 s15, s15, s14
	s_cmp_lt_i32 s15, s98
	s_cbranch_scc0 .Lxn_try4
	s_mov_b32 s58, s14
	s_add_i32 s60, s58, 0xffffc000
	s_cmpk_lt_i32 s58, 0x4000
	s_cselect_b32 s54, s48, s50
	s_cselect_b32 s55, s49, s51
	s_cselect_b32 s59, s58, s60
	s_lshl_b32 s59, s59, 12
	s_add_u32 s54, s54, s59
	s_addc_u32 s55, s55, 0
	global_load_dwordx4 v[64:67], v4, s[54:55] nt
	global_load_dwordx4 v[68:71], v4, s[54:55] offset:1024 nt
	global_load_dwordx4 v[72:75], v4, s[54:55] offset:2048 nt
	global_load_dwordx4 v[76:79], v4, s[54:55] offset:3072 nt
	s_add_i32 s58, s58, s99
	s_add_i32 s60, s58, 0xffffc000
	s_cmpk_lt_i32 s58, 0x4000
	s_cselect_b32 s54, s48, s50
	s_cselect_b32 s55, s49, s51
	s_cselect_b32 s59, s58, s60
	s_lshl_b32 s59, s59, 12
	s_add_u32 s54, s54, s59
	s_addc_u32 s55, s55, 0
	global_load_dwordx4 v[80:83], v4, s[54:55] nt
	global_load_dwordx4 v[84:87], v4, s[54:55] offset:1024 nt
	global_load_dwordx4 v[88:91], v4, s[54:55] offset:2048 nt
	global_load_dwordx4 v[92:95], v4, s[54:55] offset:3072 nt
	s_add_i32 s58, s58, s99
	s_add_i32 s60, s58, 0xffffc000
	s_cmpk_lt_i32 s58, 0x4000
	s_cselect_b32 s54, s48, s50
	s_cselect_b32 s55, s49, s51
	s_cselect_b32 s59, s58, s60
	s_lshl_b32 s59, s59, 12
	s_add_u32 s54, s54, s59
	s_addc_u32 s55, s55, 0
	global_load_dwordx4 v[96:99], v4, s[54:55] nt
	global_load_dwordx4 v[100:103], v4, s[54:55] offset:1024 nt
	global_load_dwordx4 v[104:107], v4, s[54:55] offset:2048 nt
	global_load_dwordx4 v[108:111], v4, s[54:55] offset:3072 nt
	s_add_i32 s58, s58, s99
	s_add_i32 s60, s58, 0xffffc000
	s_cmpk_lt_i32 s58, 0x4000
	s_cselect_b32 s54, s48, s50
	s_cselect_b32 s55, s49, s51
	s_cselect_b32 s59, s58, s60
	s_lshl_b32 s59, s59, 12
	s_add_u32 s54, s54, s59
	s_addc_u32 s55, s55, 0
	global_load_dwordx4 v[112:115], v4, s[54:55] nt
	global_load_dwordx4 v[116:119], v4, s[54:55] offset:1024 nt
	global_load_dwordx4 v[120:123], v4, s[54:55] offset:2048 nt
	global_load_dwordx4 v[124:127], v4, s[54:55] offset:3072 nt
	s_add_i32 s58, s58, s99
	s_add_i32 s60, s58, 0xffffc000
	s_cmpk_lt_i32 s58, 0x4000
	s_cselect_b32 s54, s48, s50
	s_cselect_b32 s55, s49, s51
	s_cselect_b32 s59, s58, s60
	s_lshl_b32 s59, s59, 12
	s_add_u32 s54, s54, s59
	s_addc_u32 s55, s55, 0
	global_load_dwordx4 v[128:131], v4, s[54:55] nt
	global_load_dwordx4 v[132:135], v4, s[54:55] offset:1024 nt
	global_load_dwordx4 v[136:139], v4, s[54:55] offset:2048 nt
	global_load_dwordx4 v[140:143], v4, s[54:55] offset:3072 nt
	s_add_i32 s58, s58, s99
	s_add_i32 s60, s58, 0xffffc000
	s_cmpk_lt_i32 s58, 0x4000
	s_cselect_b32 s54, s48, s50
	s_cselect_b32 s55, s49, s51
	s_cselect_b32 s59, s58, s60
	s_lshl_b32 s59, s59, 12
	s_add_u32 s54, s54, s59
	s_addc_u32 s55, s55, 0
	global_load_dwordx4 v[144:147], v4, s[54:55] nt
	global_load_dwordx4 v[148:151], v4, s[54:55] offset:1024 nt
	global_load_dwordx4 v[152:155], v4, s[54:55] offset:2048 nt
	global_load_dwordx4 v[156:159], v4, s[54:55] offset:3072 nt
	s_add_i32 s58, s58, s99
	s_add_i32 s60, s58, 0xffffc000
	s_cmpk_lt_i32 s58, 0x4000
	s_cselect_b32 s54, s48, s50
	s_cselect_b32 s55, s49, s51
	s_cselect_b32 s59, s58, s60
	s_lshl_b32 s59, s59, 12
	s_add_u32 s54, s54, s59
	s_addc_u32 s55, s55, 0
	global_load_dwordx4 v[160:163], v4, s[54:55] nt
	global_load_dwordx4 v[164:167], v4, s[54:55] offset:1024 nt
	global_load_dwordx4 v[168:171], v4, s[54:55] offset:2048 nt
	global_load_dwordx4 v[172:175], v4, s[54:55] offset:3072 nt
	s_add_i32 s58, s58, s99
	s_add_i32 s60, s58, 0xffffc000
	s_cmpk_lt_i32 s58, 0x4000
	s_cselect_b32 s54, s48, s50
	s_cselect_b32 s55, s49, s51
	s_cselect_b32 s59, s58, s60
	s_lshl_b32 s59, s59, 12
	s_add_u32 s54, s54, s59
	s_addc_u32 s55, s55, 0
	global_load_dwordx4 v[176:179], v4, s[54:55] nt
	global_load_dwordx4 v[180:183], v4, s[54:55] offset:1024 nt
	global_load_dwordx4 v[184:187], v4, s[54:55] offset:2048 nt
	global_load_dwordx4 v[188:191], v4, s[54:55] offset:3072 nt
	s_mov_b32 s58, s14
	s_lshl_b32 s59, s58, 11
	s_add_u32 s56, s46, s59
	s_addc_u32 s57, s47, 0
	s_waitcnt vmcnt(28)
	v_pk_mul_f32 v[192:193], v[64:65], v[64:65]
	v_pk_fma_f32 v[192:193], v[66:67], v[66:67], v[192:193]
	v_pk_fma_f32 v[192:193], v[68:69], v[68:69], v[192:193]
	v_pk_fma_f32 v[192:193], v[70:71], v[70:71], v[192:193]
	v_pk_fma_f32 v[192:193], v[72:73], v[72:73], v[192:193]
	v_pk_fma_f32 v[192:193], v[74:75], v[74:75], v[192:193]
	v_pk_fma_f32 v[192:193], v[76:77], v[76:77], v[192:193]
	v_pk_fma_f32 v[192:193], v[78:79], v[78:79], v[192:193]
	v_cvt_pk_bf16_f32 v64, v64, v65
	v_cvt_pk_bf16_f32 v65, v66, v67
	global_store_dwordx2 v5, v[64:65], s[56:57]
	v_cvt_pk_bf16_f32 v68, v68, v69
	v_cvt_pk_bf16_f32 v69, v70, v71
	global_store_dwordx2 v5, v[68:69], s[56:57] offset:512
	v_cvt_pk_bf16_f32 v72, v72, v73
	v_cvt_pk_bf16_f32 v73, v74, v75
	global_store_dwordx2 v5, v[72:73], s[56:57] offset:1024
	v_cvt_pk_bf16_f32 v76, v76, v77
	v_cvt_pk_bf16_f32 v77, v78, v79
	global_store_dwordx2 v5, v[76:77], s[56:57] offset:1536
	v_add_f32_e32 v192, v192, v193
	s_add_i32 s58, s58, s99
	s_lshl_b32 s59, s58, 11
	s_add_u32 s56, s46, s59
	s_addc_u32 s57, s47, 0
	s_waitcnt vmcnt(28)
	v_pk_mul_f32 v[194:195], v[80:81], v[80:81]
	v_pk_fma_f32 v[194:195], v[82:83], v[82:83], v[194:195]
	v_pk_fma_f32 v[194:195], v[84:85], v[84:85], v[194:195]
	v_pk_fma_f32 v[194:195], v[86:87], v[86:87], v[194:195]
	v_pk_fma_f32 v[194:195], v[88:89], v[88:89], v[194:195]
	v_pk_fma_f32 v[194:195], v[90:91], v[90:91], v[194:195]
	v_pk_fma_f32 v[194:195], v[92:93], v[92:93], v[194:195]
	v_pk_fma_f32 v[194:195], v[94:95], v[94:95], v[194:195]
	v_cvt_pk_bf16_f32 v80, v80, v81
	v_cvt_pk_bf16_f32 v81, v82, v83
	global_store_dwordx2 v5, v[80:81], s[56:57]
	v_cvt_pk_bf16_f32 v84, v84, v85
	v_cvt_pk_bf16_f32 v85, v86, v87
	global_store_dwordx2 v5, v[84:85], s[56:57] offset:512
	v_cvt_pk_bf16_f32 v88, v88, v89
	v_cvt_pk_bf16_f32 v89, v90, v91
	global_store_dwordx2 v5, v[88:89], s[56:57] offset:1024
	v_cvt_pk_bf16_f32 v92, v92, v93
	v_cvt_pk_bf16_f32 v93, v94, v95
	global_store_dwordx2 v5, v[92:93], s[56:57] offset:1536
	v_add_f32_e32 v194, v194, v195
	s_add_i32 s58, s58, s99
	s_lshl_b32 s59, s58, 11
	s_add_u32 s56, s46, s59
	s_addc_u32 s57, s47, 0
	s_waitcnt vmcnt(28)
	v_pk_mul_f32 v[196:197], v[96:97], v[96:97]
	v_pk_fma_f32 v[196:197], v[98:99], v[98:99], v[196:197]
	v_pk_fma_f32 v[196:197], v[100:101], v[100:101], v[196:197]
	v_pk_fma_f32 v[196:197], v[102:103], v[102:103], v[196:197]
	v_pk_fma_f32 v[196:197], v[104:105], v[104:105], v[196:197]
	v_pk_fma_f32 v[196:197], v[106:107], v[106:107], v[196:197]
	v_pk_fma_f32 v[196:197], v[108:109], v[108:109], v[196:197]
	v_pk_fma_f32 v[196:197], v[110:111], v[110:111], v[196:197]
	v_cvt_pk_bf16_f32 v96, v96, v97
	v_cvt_pk_bf16_f32 v97, v98, v99
	global_store_dwordx2 v5, v[96:97], s[56:57]
	v_cvt_pk_bf16_f32 v100, v100, v101
	v_cvt_pk_bf16_f32 v101, v102, v103
	global_store_dwordx2 v5, v[100:101], s[56:57] offset:512
	v_cvt_pk_bf16_f32 v104, v104, v105
	v_cvt_pk_bf16_f32 v105, v106, v107
	global_store_dwordx2 v5, v[104:105], s[56:57] offset:1024
	v_cvt_pk_bf16_f32 v108, v108, v109
	v_cvt_pk_bf16_f32 v109, v110, v111
	global_store_dwordx2 v5, v[108:109], s[56:57] offset:1536
	v_add_f32_e32 v196, v196, v197
	s_add_i32 s58, s58, s99
	s_lshl_b32 s59, s58, 11
	s_add_u32 s56, s46, s59
	s_addc_u32 s57, s47, 0
	s_waitcnt vmcnt(28)
	v_pk_mul_f32 v[198:199], v[112:113], v[112:113]
	v_pk_fma_f32 v[198:199], v[114:115], v[114:115], v[198:199]
	v_pk_fma_f32 v[198:199], v[116:117], v[116:117], v[198:199]
	v_pk_fma_f32 v[198:199], v[118:119], v[118:119], v[198:199]
	v_pk_fma_f32 v[198:199], v[120:121], v[120:121], v[198:199]
	v_pk_fma_f32 v[198:199], v[122:123], v[122:123], v[198:199]
	v_pk_fma_f32 v[198:199], v[124:125], v[124:125], v[198:199]
	v_pk_fma_f32 v[198:199], v[126:127], v[126:127], v[198:199]
	v_cvt_pk_bf16_f32 v112, v112, v113
	v_cvt_pk_bf16_f32 v113, v114, v115
	global_store_dwordx2 v5, v[112:113], s[56:57]
	v_cvt_pk_bf16_f32 v116, v116, v117
	v_cvt_pk_bf16_f32 v117, v118, v119
	global_store_dwordx2 v5, v[116:117], s[56:57] offset:512
	v_cvt_pk_bf16_f32 v120, v120, v121
	v_cvt_pk_bf16_f32 v121, v122, v123
	global_store_dwordx2 v5, v[120:121], s[56:57] offset:1024
	v_cvt_pk_bf16_f32 v124, v124, v125
	v_cvt_pk_bf16_f32 v125, v126, v127
	global_store_dwordx2 v5, v[124:125], s[56:57] offset:1536
	v_add_f32_e32 v198, v198, v199
	s_add_i32 s58, s58, s99
	s_lshl_b32 s59, s58, 11
	s_add_u32 s56, s46, s59
	s_addc_u32 s57, s47, 0
	s_waitcnt vmcnt(28)
	v_pk_mul_f32 v[200:201], v[128:129], v[128:129]
	v_pk_fma_f32 v[200:201], v[130:131], v[130:131], v[200:201]
	v_pk_fma_f32 v[200:201], v[132:133], v[132:133], v[200:201]
	v_pk_fma_f32 v[200:201], v[134:135], v[134:135], v[200:201]
	v_pk_fma_f32 v[200:201], v[136:137], v[136:137], v[200:201]
	v_pk_fma_f32 v[200:201], v[138:139], v[138:139], v[200:201]
	v_pk_fma_f32 v[200:201], v[140:141], v[140:141], v[200:201]
	v_pk_fma_f32 v[200:201], v[142:143], v[142:143], v[200:201]
	v_cvt_pk_bf16_f32 v128, v128, v129
	v_cvt_pk_bf16_f32 v129, v130, v131
	global_store_dwordx2 v5, v[128:129], s[56:57]
	v_cvt_pk_bf16_f32 v132, v132, v133
	v_cvt_pk_bf16_f32 v133, v134, v135
	global_store_dwordx2 v5, v[132:133], s[56:57] offset:512
	v_cvt_pk_bf16_f32 v136, v136, v137
	v_cvt_pk_bf16_f32 v137, v138, v139
	global_store_dwordx2 v5, v[136:137], s[56:57] offset:1024
	v_cvt_pk_bf16_f32 v140, v140, v141
	v_cvt_pk_bf16_f32 v141, v142, v143
	global_store_dwordx2 v5, v[140:141], s[56:57] offset:1536
	v_add_f32_e32 v200, v200, v201
	s_add_i32 s58, s58, s99
	s_lshl_b32 s59, s58, 11
	s_add_u32 s56, s46, s59
	s_addc_u32 s57, s47, 0
	s_waitcnt vmcnt(28)
	v_pk_mul_f32 v[202:203], v[144:145], v[144:145]
	v_pk_fma_f32 v[202:203], v[146:147], v[146:147], v[202:203]
	v_pk_fma_f32 v[202:203], v[148:149], v[148:149], v[202:203]
	v_pk_fma_f32 v[202:203], v[150:151], v[150:151], v[202:203]
	v_pk_fma_f32 v[202:203], v[152:153], v[152:153], v[202:203]
	v_pk_fma_f32 v[202:203], v[154:155], v[154:155], v[202:203]
	v_pk_fma_f32 v[202:203], v[156:157], v[156:157], v[202:203]
	v_pk_fma_f32 v[202:203], v[158:159], v[158:159], v[202:203]
	v_cvt_pk_bf16_f32 v144, v144, v145
	v_cvt_pk_bf16_f32 v145, v146, v147
	global_store_dwordx2 v5, v[144:145], s[56:57]
	v_cvt_pk_bf16_f32 v148, v148, v149
	v_cvt_pk_bf16_f32 v149, v150, v151
	global_store_dwordx2 v5, v[148:149], s[56:57] offset:512
	v_cvt_pk_bf16_f32 v152, v152, v153
	v_cvt_pk_bf16_f32 v153, v154, v155
	global_store_dwordx2 v5, v[152:153], s[56:57] offset:1024
	v_cvt_pk_bf16_f32 v156, v156, v157
	v_cvt_pk_bf16_f32 v157, v158, v159
	global_store_dwordx2 v5, v[156:157], s[56:57] offset:1536
	v_add_f32_e32 v202, v202, v203
	s_add_i32 s58, s58, s99
	s_lshl_b32 s59, s58, 11
	s_add_u32 s56, s46, s59
	s_addc_u32 s57, s47, 0
	s_waitcnt vmcnt(28)
	v_pk_mul_f32 v[204:205], v[160:161], v[160:161]
	v_pk_fma_f32 v[204:205], v[162:163], v[162:163], v[204:205]
	v_pk_fma_f32 v[204:205], v[164:165], v[164:165], v[204:205]
	v_pk_fma_f32 v[204:205], v[166:167], v[166:167], v[204:205]
	v_pk_fma_f32 v[204:205], v[168:169], v[168:169], v[204:205]
	v_pk_fma_f32 v[204:205], v[170:171], v[170:171], v[204:205]
	v_pk_fma_f32 v[204:205], v[172:173], v[172:173], v[204:205]
	v_pk_fma_f32 v[204:205], v[174:175], v[174:175], v[204:205]
	v_cvt_pk_bf16_f32 v160, v160, v161
	v_cvt_pk_bf16_f32 v161, v162, v163
	global_store_dwordx2 v5, v[160:161], s[56:57]
	v_cvt_pk_bf16_f32 v164, v164, v165
	v_cvt_pk_bf16_f32 v165, v166, v167
	global_store_dwordx2 v5, v[164:165], s[56:57] offset:512
	v_cvt_pk_bf16_f32 v168, v168, v169
	v_cvt_pk_bf16_f32 v169, v170, v171
	global_store_dwordx2 v5, v[168:169], s[56:57] offset:1024
	v_cvt_pk_bf16_f32 v172, v172, v173
	v_cvt_pk_bf16_f32 v173, v174, v175
	global_store_dwordx2 v5, v[172:173], s[56:57] offset:1536
	v_add_f32_e32 v204, v204, v205
	s_add_i32 s58, s58, s99
	s_lshl_b32 s59, s58, 11
	s_add_u32 s56, s46, s59
	s_addc_u32 s57, s47, 0
	s_waitcnt vmcnt(28)
	v_pk_mul_f32 v[206:207], v[176:177], v[176:177]
	v_pk_fma_f32 v[206:207], v[178:179], v[178:179], v[206:207]
	v_pk_fma_f32 v[206:207], v[180:181], v[180:181], v[206:207]
	v_pk_fma_f32 v[206:207], v[182:183], v[182:183], v[206:207]
	v_pk_fma_f32 v[206:207], v[184:185], v[184:185], v[206:207]
	v_pk_fma_f32 v[206:207], v[186:187], v[186:187], v[206:207]
	v_pk_fma_f32 v[206:207], v[188:189], v[188:189], v[206:207]
	v_pk_fma_f32 v[206:207], v[190:191], v[190:191], v[206:207]
	v_cvt_pk_bf16_f32 v176, v176, v177
	v_cvt_pk_bf16_f32 v177, v178, v179
	global_store_dwordx2 v5, v[176:177], s[56:57]
	v_cvt_pk_bf16_f32 v180, v180, v181
	v_cvt_pk_bf16_f32 v181, v182, v183
	global_store_dwordx2 v5, v[180:181], s[56:57] offset:512
	v_cvt_pk_bf16_f32 v184, v184, v185
	v_cvt_pk_bf16_f32 v185, v186, v187
	global_store_dwordx2 v5, v[184:185], s[56:57] offset:1024
	v_cvt_pk_bf16_f32 v188, v188, v189
	v_cvt_pk_bf16_f32 v189, v190, v191
	global_store_dwordx2 v5, v[188:189], s[56:57] offset:1536
	v_add_f32_e32 v206, v206, v207
	ds_bpermute_b32 v193, v6, v192
	ds_bpermute_b32 v195, v6, v194
	ds_bpermute_b32 v197, v6, v196
	ds_bpermute_b32 v199, v6, v198
	ds_bpermute_b32 v201, v6, v200
	ds_bpermute_b32 v203, v6, v202
	ds_bpermute_b32 v205, v6, v204
	ds_bpermute_b32 v207, v6, v206
	s_waitcnt lgkmcnt(0)
	v_add_f32_e32 v192, v192, v193
	v_add_f32_e32 v194, v194, v195
	v_add_f32_e32 v196, v196, v197
	v_add_f32_e32 v198, v198, v199
	v_add_f32_e32 v200, v200, v201
	v_add_f32_e32 v202, v202, v203
	v_add_f32_e32 v204, v204, v205
	v_add_f32_e32 v206, v206, v207
	ds_bpermute_b32 v193, v7, v192
	ds_bpermute_b32 v195, v7, v194
	ds_bpermute_b32 v197, v7, v196
	ds_bpermute_b32 v199, v7, v198
	ds_bpermute_b32 v201, v7, v200
	ds_bpermute_b32 v203, v7, v202
	ds_bpermute_b32 v205, v7, v204
	ds_bpermute_b32 v207, v7, v206
	s_waitcnt lgkmcnt(0)
	v_add_f32_e32 v192, v192, v193
	v_add_f32_e32 v194, v194, v195
	v_add_f32_e32 v196, v196, v197
	v_add_f32_e32 v198, v198, v199
	v_add_f32_e32 v200, v200, v201
	v_add_f32_e32 v202, v202, v203
	v_add_f32_e32 v204, v204, v205
	v_add_f32_e32 v206, v206, v207
	ds_bpermute_b32 v193, v8, v192
	ds_bpermute_b32 v195, v8, v194
	ds_bpermute_b32 v197, v8, v196
	ds_bpermute_b32 v199, v8, v198
	ds_bpermute_b32 v201, v8, v200
	ds_bpermute_b32 v203, v8, v202
	ds_bpermute_b32 v205, v8, v204
	ds_bpermute_b32 v207, v8, v206
	s_waitcnt lgkmcnt(0)
	v_add_f32_e32 v192, v192, v193
	v_add_f32_e32 v194, v194, v195
	v_add_f32_e32 v196, v196, v197
	v_add_f32_e32 v198, v198, v199
	v_add_f32_e32 v200, v200, v201
	v_add_f32_e32 v202, v202, v203
	v_add_f32_e32 v204, v204, v205
	v_add_f32_e32 v206, v206, v207
	ds_bpermute_b32 v193, v9, v192
	ds_bpermute_b32 v195, v9, v194
	ds_bpermute_b32 v197, v9, v196
	ds_bpermute_b32 v199, v9, v198
	ds_bpermute_b32 v201, v9, v200
	ds_bpermute_b32 v203, v9, v202
	ds_bpermute_b32 v205, v9, v204
	ds_bpermute_b32 v207, v9, v206
	s_waitcnt lgkmcnt(0)
	v_add_f32_e32 v192, v192, v193
	v_add_f32_e32 v194, v194, v195
	v_add_f32_e32 v196, v196, v197
	v_add_f32_e32 v198, v198, v199
	v_add_f32_e32 v200, v200, v201
	v_add_f32_e32 v202, v202, v203
	v_add_f32_e32 v204, v204, v205
	v_add_f32_e32 v206, v206, v207
	ds_bpermute_b32 v193, v10, v192
	ds_bpermute_b32 v195, v10, v194
	ds_bpermute_b32 v197, v10, v196
	ds_bpermute_b32 v199, v10, v198
	ds_bpermute_b32 v201, v10, v200
	ds_bpermute_b32 v203, v10, v202
	ds_bpermute_b32 v205, v10, v204
	ds_bpermute_b32 v207, v10, v206
	s_waitcnt lgkmcnt(0)
	v_add_f32_e32 v192, v192, v193
	v_add_f32_e32 v194, v194, v195
	v_add_f32_e32 v196, v196, v197
	v_add_f32_e32 v198, v198, v199
	v_add_f32_e32 v200, v200, v201
	v_add_f32_e32 v202, v202, v203
	v_add_f32_e32 v204, v204, v205
	v_add_f32_e32 v206, v206, v207
	ds_bpermute_b32 v193, v11, v192
	ds_bpermute_b32 v195, v11, v194
	ds_bpermute_b32 v197, v11, v196
	ds_bpermute_b32 v199, v11, v198
	ds_bpermute_b32 v201, v11, v200
	ds_bpermute_b32 v203, v11, v202
	ds_bpermute_b32 v205, v11, v204
	ds_bpermute_b32 v207, v11, v206
	s_waitcnt lgkmcnt(0)
	v_add_f32_e32 v192, v192, v193
	v_add_f32_e32 v194, v194, v195
	v_add_f32_e32 v196, v196, v197
	v_add_f32_e32 v198, v198, v199
	v_add_f32_e32 v200, v200, v201
	v_add_f32_e32 v202, v202, v203
	v_add_f32_e32 v204, v204, v205
	v_add_f32_e32 v206, v206, v207
	s_mov_b64 exec, 1
	s_mov_b32 s58, s14
	s_lshl_b32 s59, s58, 2
	s_add_u32 s56, s52, s59
	s_addc_u32 s57, s53, 0
	global_store_dword v12, v192, s[56:57]
	s_add_i32 s58, s58, s99
	s_lshl_b32 s59, s58, 2
	s_add_u32 s56, s52, s59
	s_addc_u32 s57, s53, 0
	global_store_dword v12, v194, s[56:57]
	s_add_i32 s58, s58, s99
	s_lshl_b32 s59, s58, 2
	s_add_u32 s56, s52, s59
	s_addc_u32 s57, s53, 0
	global_store_dword v12, v196, s[56:57]
	s_add_i32 s58, s58, s99
	s_lshl_b32 s59, s58, 2
	s_add_u32 s56, s52, s59
	s_addc_u32 s57, s53, 0
	global_store_dword v12, v198, s[56:57]
	s_add_i32 s58, s58, s99
	s_lshl_b32 s59, s58, 2
	s_add_u32 s56, s52, s59
	s_addc_u32 s57, s53, 0
	global_store_dword v12, v200, s[56:57]
	s_add_i32 s58, s58, s99
	s_lshl_b32 s59, s58, 2
	s_add_u32 s56, s52, s59
	s_addc_u32 s57, s53, 0
	global_store_dword v12, v202, s[56:57]
	s_add_i32 s58, s58, s99
	s_lshl_b32 s59, s58, 2
	s_add_u32 s56, s52, s59
	s_addc_u32 s57, s53, 0
	global_store_dword v12, v204, s[56:57]
	s_add_i32 s58, s58, s99
	s_lshl_b32 s59, s58, 2
	s_add_u32 s56, s52, s59
	s_addc_u32 s57, s53, 0
	global_store_dword v12, v206, s[56:57]
	s_mov_b64 exec, -1
	s_lshl_b32 s15, s99, 3
	s_add_i32 s14, s14, s15
	s_branch .Lxn_loop
